# phase_final: next-row-B loads into own staging regs, wait deferred to next iteration (restores 2-row-ahead prefetch)
# speedup vs baseline: 1.0060x; 1.0060x over previous
.LBB0_2580:
	v_readlane_b32 s2, v254, 14
	s_add_i32 s2, s10, s2
	s_cmpk_gt_i32 s2, 0x3fff
	v_readlane_b32 s16, v253, 47
	v_readlane_b32 s17, v253, 48
	s_cbranch_scc1 .LBB0_2582
	s_ashr_i32 s3, s2, 31
	s_lshl_b64 s[2:3], s[2:3], 12
	s_add_u32 s2, s6, s2
	s_addc_u32 s3, s7, s3
	global_load_dwordx2 v[70:71], v22, s[2:3]
	global_load_dwordx2 v[72:73], v22, s[2:3] offset:512
	global_load_dwordx2 v[74:75], v22, s[2:3] offset:1024
	global_load_dwordx2 v[76:77], v22, s[2:3] offset:1536

.LBB0_2584:
	v_lshlrev_b32_e32 v48, 16, v36
	v_and_b32_e32 v49, 0xffff0000, v36
	v_lshlrev_b32_e32 v36, 16, v37
	v_and_b32_e32 v37, 0xffff0000, v37
	v_mul_f32_e32 v50, v49, v49
	v_mul_f32_e32 v51, v37, v37
	v_fmac_f32_e32 v50, v48, v48
	v_fmac_f32_e32 v51, v36, v36
	v_add_f32_e32 v52, v50, v51
	v_lshlrev_b32_e32 v50, 16, v34
	v_and_b32_e32 v51, 0xffff0000, v34
	v_lshlrev_b32_e32 v34, 16, v35
	v_and_b32_e32 v35, 0xffff0000, v35
	v_mul_f32_e32 v53, v51, v51
	v_mul_f32_e32 v54, v35, v35
	v_fmac_f32_e32 v53, v50, v50
	v_fmac_f32_e32 v54, v34, v34
	v_add_f32_e32 v53, v53, v54
	v_add_f32_e32 v56, v53, v52
	v_and_b32_e32 v53, 0xffff0000, v32
	v_and_b32_e32 v55, 0xffff0000, v33
	v_lshlrev_b32_e32 v52, 16, v32
	v_lshlrev_b32_e32 v54, 16, v33
	v_mul_f32_e32 v32, v53, v53
	v_mul_f32_e32 v33, v55, v55
	v_fmac_f32_e32 v32, v52, v52
	v_fmac_f32_e32 v33, v54, v54
	v_add_f32_e32 v32, v32, v33
	v_and_b32_e32 v57, 0xffff0000, v30
	v_and_b32_e32 v59, 0xffff0000, v31
	v_add_f32_e32 v32, v32, v56
	v_lshlrev_b32_e32 v56, 16, v30
	v_lshlrev_b32_e32 v58, 16, v31
	v_mul_f32_e32 v30, v57, v57
	v_mul_f32_e32 v31, v59, v59
	v_fmac_f32_e32 v30, v56, v56
	v_fmac_f32_e32 v31, v58, v58
	v_add_f32_e32 v30, v30, v31
	v_add_f32_e32 v30, v30, v32
	ds_swizzle_b32 v31, v30 offset:swizzle(SWAP,1)
	s_ashr_i32 s5, s4, 31
	s_lshl_b64 s[10:11], s[4:5], 12
	v_lshl_add_u64 v[62:63], v[18:19], 0, s[10:11]
	v_lshl_add_u64 v[20:21], v[20:21], 0, s[2:3]
	s_waitcnt lgkmcnt(0)
	v_add_f32_e32 v30, v30, v31
	ds_swizzle_b32 v31, v30 offset:swizzle(SWAP,2)
	s_add_i32 s4, s4, s16
	s_mov_b64 s[12:13], s[8:9]
	s_waitcnt lgkmcnt(0)
	v_add_f32_e32 v30, v30, v31
	ds_swizzle_b32 v31, v30 offset:swizzle(SWAP,4)
	s_waitcnt lgkmcnt(0)
	v_add_f32_e32 v30, v30, v31
	ds_swizzle_b32 v31, v30 offset:swizzle(SWAP,8)
	s_waitcnt lgkmcnt(0)
	v_add_f32_e32 v30, v30, v31
	ds_swizzle_b32 v31, v30 offset:swizzle(SWAP,16)
	s_waitcnt lgkmcnt(0)
	v_add_f32_e32 v30, v30, v31
	v_mov_b32_e32 v31, v30
	s_nop 1
	v_permlane32_swap_b32_e32 v30, v31
	v_add_f32_e32 v30, v30, v31
	v_fmamk_f32 v30, v30, 0x3a800000, v46
	v_mul_f32_e32 v31, 0x4b800000, v30
	v_cmp_gt_f32_e32 vcc, s14, v30
	s_nop 1
	v_cndmask_b32_e32 v30, v30, v31, vcc
	v_rsq_f32_e32 v30, v30
	s_nop 0
	v_mul_f32_e32 v31, 0x45800000, v30
	v_cndmask_b32_e32 v60, v30, v31, vcc
	v_pk_mul_f32 v[30:31], v[36:37], v[60:61] op_sel_hi:[1,0]
	v_pk_mul_f32 v[32:33], v[48:49], v[60:61] op_sel_hi:[1,0]
	v_pk_mul_f32 v[30:31], v[2:3], v[30:31]
	v_pk_mul_f32 v[36:37], v[0:1], v[32:33]
	v_cndmask_b32_e64 v33, v47, v31, s[0:1]
	v_cndmask_b32_e64 v32, v47, v30, s[0:1]
	v_cndmask_b32_e64 v31, v47, v37, s[0:1]
	v_cndmask_b32_e64 v30, v47, v36, s[0:1]
	global_store_dwordx4 v[62:63], v[30:33], off
	s_nop 1
	v_pk_mul_f32 v[30:31], v[34:35], v[60:61] op_sel_hi:[1,0]
	v_pk_mul_f32 v[32:33], v[50:51], v[60:61] op_sel_hi:[1,0]
	v_pk_mul_f32 v[30:31], v[6:7], v[30:31]
	v_pk_mul_f32 v[34:35], v[4:5], v[32:33]
	v_cndmask_b32_e64 v33, v47, v31, s[0:1]
	v_cndmask_b32_e64 v32, v47, v30, s[0:1]
	v_cndmask_b32_e64 v31, v47, v35, s[0:1]
	v_cndmask_b32_e64 v30, v47, v34, s[0:1]
	global_store_dwordx4 v[62:63], v[30:33], off offset:1024
	s_nop 1
	v_pk_mul_f32 v[30:31], v[54:55], v[60:61] op_sel_hi:[1,0]
	v_pk_mul_f32 v[32:33], v[52:53], v[60:61] op_sel_hi:[1,0]
	v_pk_mul_f32 v[30:31], v[10:11], v[30:31]
	v_pk_mul_f32 v[34:35], v[8:9], v[32:33]
	v_cndmask_b32_e64 v33, v47, v31, s[0:1]
	v_cndmask_b32_e64 v32, v47, v30, s[0:1]
	v_cndmask_b32_e64 v31, v47, v35, s[0:1]
	v_cndmask_b32_e64 v30, v47, v34, s[0:1]
	global_store_dwordx4 v[62:63], v[30:33], off offset:2048
	s_nop 1
	v_pk_mul_f32 v[30:31], v[58:59], v[60:61] op_sel_hi:[1,0]
	v_pk_mul_f32 v[32:33], v[56:57], v[60:61] op_sel_hi:[1,0]
	v_pk_mul_f32 v[30:31], v[14:15], v[30:31]
	v_pk_mul_f32 v[34:35], v[12:13], v[32:33]
	v_cndmask_b32_e64 v33, v47, v31, s[0:1]
	v_cndmask_b32_e64 v32, v47, v30, s[0:1]
	v_cndmask_b32_e64 v31, v47, v35, s[0:1]
	v_cndmask_b32_e64 v30, v47, v34, s[0:1]
	global_store_dwordx4 v[62:63], v[30:33], off offset:3072
.LBB0_2585:
	s_and_b64 vcc, exec, s[12:13]
	s_waitcnt vmcnt(8)
	v_mov_b64_e32 v[44:45], v[22:23]
	v_mov_b64_e32 v[42:43], v[24:25]
	v_mov_b64_e32 v[40:41], v[26:27]
	v_mov_b64_e32 v[38:39], v[28:29]
	s_mov_b32 s10, s6
	s_cbranch_vccnz .LBB0_2591

.LBB0_2588:
	v_lshlrev_b32_e32 v48, 16, v44
	v_and_b32_e32 v49, 0xffff0000, v44
	v_lshlrev_b32_e32 v44, 16, v45
	v_and_b32_e32 v45, 0xffff0000, v45
	v_mul_f32_e32 v50, v49, v49
	v_mul_f32_e32 v51, v45, v45
	v_fmac_f32_e32 v50, v48, v48
	v_fmac_f32_e32 v51, v44, v44
	v_add_f32_e32 v52, v50, v51
	v_lshlrev_b32_e32 v50, 16, v42
	v_and_b32_e32 v51, 0xffff0000, v42
	v_lshlrev_b32_e32 v42, 16, v43
	v_and_b32_e32 v43, 0xffff0000, v43
	v_mul_f32_e32 v53, v51, v51
	v_mul_f32_e32 v54, v43, v43
	v_fmac_f32_e32 v53, v50, v50
	v_fmac_f32_e32 v54, v42, v42
	v_add_f32_e32 v53, v53, v54
	v_add_f32_e32 v56, v52, v53
	v_and_b32_e32 v53, 0xffff0000, v40
	v_and_b32_e32 v55, 0xffff0000, v41
	v_lshlrev_b32_e32 v52, 16, v40
	v_lshlrev_b32_e32 v54, 16, v41
	v_mul_f32_e32 v40, v53, v53
	v_mul_f32_e32 v41, v55, v55
	v_fmac_f32_e32 v40, v52, v52
	v_fmac_f32_e32 v41, v54, v54
	v_add_f32_e32 v40, v40, v41
	v_and_b32_e32 v57, 0xffff0000, v38
	v_and_b32_e32 v59, 0xffff0000, v39
	v_add_f32_e32 v40, v56, v40
	v_lshlrev_b32_e32 v56, 16, v38
	v_lshlrev_b32_e32 v58, 16, v39
	v_mul_f32_e32 v38, v57, v57
	v_mul_f32_e32 v39, v59, v59
	v_fmac_f32_e32 v38, v56, v56
	v_fmac_f32_e32 v39, v58, v58
	v_add_f32_e32 v38, v38, v39
	v_add_f32_e32 v38, v40, v38
	ds_swizzle_b32 v39, v38 offset:swizzle(SWAP,1)
	s_cmpk_gt_i32 s4, 0x3fff
	s_mov_b64 s[12:13], -1
	s_waitcnt lgkmcnt(0)
	v_add_f32_e32 v38, v38, v39
	ds_swizzle_b32 v39, v38 offset:swizzle(SWAP,2)
	s_waitcnt lgkmcnt(0)
	v_add_f32_e32 v38, v38, v39
	ds_swizzle_b32 v39, v38 offset:swizzle(SWAP,4)
	s_waitcnt lgkmcnt(0)
	v_add_f32_e32 v38, v38, v39
	ds_swizzle_b32 v39, v38 offset:swizzle(SWAP,8)
	s_waitcnt lgkmcnt(0)
	v_add_f32_e32 v38, v38, v39
	ds_swizzle_b32 v39, v38 offset:swizzle(SWAP,16)
	s_waitcnt lgkmcnt(0)
	v_add_f32_e32 v38, v38, v39
	v_mov_b32_e32 v39, v38
	s_nop 1
	v_permlane32_swap_b32_e32 v38, v39
	v_add_f32_e32 v38, v38, v39
	v_fmamk_f32 v38, v38, 0x3a800000, v46
	v_mul_f32_e32 v39, 0x4b800000, v38
	v_cmp_gt_f32_e32 vcc, s14, v38
	s_nop 1
	v_cndmask_b32_e32 v38, v38, v39, vcc
	v_rsq_f32_e32 v38, v38
	s_nop 0
	v_mul_f32_e32 v39, 0x45800000, v38
	v_cndmask_b32_e32 v60, v38, v39, vcc
	v_pk_mul_f32 v[38:39], v[44:45], v[60:61] op_sel_hi:[1,0]
	v_pk_mul_f32 v[40:41], v[48:49], v[60:61] op_sel_hi:[1,0]
	v_pk_mul_f32 v[38:39], v[2:3], v[38:39]
	v_pk_mul_f32 v[44:45], v[0:1], v[40:41]
	v_cndmask_b32_e64 v41, v47, v39, s[0:1]
	v_cndmask_b32_e64 v40, v47, v38, s[0:1]
	v_cndmask_b32_e64 v39, v47, v45, s[0:1]
	v_cndmask_b32_e64 v38, v47, v44, s[0:1]
	global_store_dwordx4 v[20:21], v[38:41], off offset:-2048
	s_nop 1
	v_pk_mul_f32 v[38:39], v[42:43], v[60:61] op_sel_hi:[1,0]
	v_pk_mul_f32 v[40:41], v[50:51], v[60:61] op_sel_hi:[1,0]
	v_pk_mul_f32 v[38:39], v[6:7], v[38:39]
	v_pk_mul_f32 v[42:43], v[4:5], v[40:41]
	v_cndmask_b32_e64 v41, v47, v39, s[0:1]
	v_cndmask_b32_e64 v40, v47, v38, s[0:1]
	v_cndmask_b32_e64 v39, v47, v43, s[0:1]
	v_cndmask_b32_e64 v38, v47, v42, s[0:1]
	global_store_dwordx4 v[20:21], v[38:41], off offset:-1024
	s_nop 1
	v_pk_mul_f32 v[38:39], v[54:55], v[60:61] op_sel_hi:[1,0]
	v_pk_mul_f32 v[40:41], v[52:53], v[60:61] op_sel_hi:[1,0]
	v_pk_mul_f32 v[38:39], v[10:11], v[38:39]
	v_pk_mul_f32 v[42:43], v[8:9], v[40:41]
	v_cndmask_b32_e64 v41, v47, v39, s[0:1]
	v_cndmask_b32_e64 v40, v47, v38, s[0:1]
	v_cndmask_b32_e64 v39, v47, v43, s[0:1]
	v_cndmask_b32_e64 v38, v47, v42, s[0:1]
	global_store_dwordx4 v[20:21], v[38:41], off
	s_nop 1
	v_pk_mul_f32 v[38:39], v[58:59], v[60:61] op_sel_hi:[1,0]
	v_pk_mul_f32 v[40:41], v[56:57], v[60:61] op_sel_hi:[1,0]
	v_pk_mul_f32 v[38:39], v[14:15], v[38:39]
	v_pk_mul_f32 v[42:43], v[12:13], v[40:41]
	v_cndmask_b32_e64 v41, v47, v39, s[0:1]
	v_cndmask_b32_e64 v40, v47, v38, s[0:1]
	v_cndmask_b32_e64 v39, v47, v43, s[0:1]
	v_cndmask_b32_e64 v38, v47, v42, s[0:1]
	global_store_dwordx4 v[20:21], v[38:41], off offset:1024
	s_cbranch_scc1 .LBB0_2585
	s_add_i32 s10, s15, s10
	s_cmpk_gt_i32 s10, 0x3fff
	s_waitcnt vmcnt(8)
	v_mov_b64_e32 v[36:37], v[70:71]
	v_mov_b64_e32 v[34:35], v[72:73]
	v_mov_b64_e32 v[32:33], v[74:75]
	v_mov_b64_e32 v[30:31], v[76:77]
	s_cbranch_scc1 .LBB0_2584
	s_ashr_i32 s11, s10, 31
	s_lshl_b64 s[10:11], s[10:11], 12
	v_lshl_add_u64 v[48:49], v[16:17], 0, s[10:11]
	global_load_dwordx2 v[70:71], v[48:49], off
	global_load_dwordx2 v[72:73], v[48:49], off offset:512
	global_load_dwordx2 v[74:75], v[48:49], off offset:1024
	global_load_dwordx2 v[76:77], v[48:49], off offset:1536
	s_branch .LBB0_2584
